# sc1 write-through stores in P2 filler transposes + DT rows halved + P2 epilogue rewrite
# speedup vs baseline: 1.0103x; 1.0103x over previous
; __device__ __forceinline__ unsigned pk2(float lo, float hi) { return pk2hw(lo, hi); }
; __global__ void __launch_bounds__(NTHR, 2) fwd_kernel(Args a) {
;     ...
;         for (int gi = gtid; gi < 2048 * 512; gi += NT) {
;             const int k1 = gi >> 9, j0 = (gi & 511) * 8; float v[8];
; #pragma unroll
;             for (int e = 0; e < 8; ++e) { const int j = j0 + e; const int ph = (k1 * (j & 2047)) & 2047; const float x = (float)ph * (1.0f / 1024.0f); v[e] = j < 2048 ? cospif(x) : -sinpif(x); }
;             u32x4 o; o.x = pk2(v[0], v[1]); o.y = pk2(v[2], v[3]); o.z = pk2(v[4], v[5]); o.w = pk2(v[6], v[7]);
;             *(u32x4*)(DT + (size_t)k1 * 4096 + j0) = o;
.LBB0_27:
	s_or_b64 exec, exec, s[2:3]
	s_add_u32 s72, s66, 0x7400000
	s_mov_b32 s1, 0x100000
	s_addc_u32 s73, s67, 0
	v_cmp_gt_i32_e32 vcc, s1, v4
	s_and_saveexec_b64 s[6:7], vcc
	s_cbranch_execz .LBB0_62
	v_lshl_add_u32 v5, s88, 12, v10
	s_lshl_b32 s1, s86, 12
	s_mov_b64 s[8:9], 0
	s_movk_i32 s14, 0x7ff
	s_mov_b32 s15, 0x7f800000
	v_mov_b32_e32 v6, 0xbf1f24be
	v_mov_b32_e32 v7, 0x3e642e9d
	s_brev_b32 s16, 1
	v_mov_b32_e32 v1, 0
	s_mov_b32 s17, 0x7ffff
	v_mov_b32_e32 v8, 0xffc00000
	v_mov_b32_e32 v9, 0x7fc00000
	v_mov_b32_e32 v11, v4
	s_branch .LBB0_30

; #define LAS __attribute__((address_space(3)))
; __device__ __forceinline__ unsigned pk2(float lo, float hi) { return pk2hw(lo, hi); }
; __device__ __forceinline__ void transpose_item(const float* W, int K, int N, bf16_t* WT, int drow0, LAS float* scr, int k0, int n0, int lane) {
;     ...
;     const int c = lane & 7;
; #pragma unroll
;     for (int j = 0; j < 4; ++j) { const int n = (lane >> 3) + 8 * j; const LAS float* s = scr + (8 * c) * 33 + n;
;         u32x4 o; o.x = pk2(s[0 * 33], s[1 * 33]); o.y = pk2(s[2 * 33], s[3 * 33]); o.z = pk2(s[4 * 33], s[5 * 33]); o.w = pk2(s[6 * 33], s[7 * 33]);
;         *(u32x4*)(WT + (size_t)(drow0 + n) * K + k0 + 8 * c) = o; }
; __global__ void __launch_bounds__(NTHR, 2) fwd_kernel(Args a) {
;     ...
;                     if (r < IT_GLA) { transpose_item(a.in[I_WGLA], VW, DM, WglaT, (r % 64) * 32, scr, (r / 64) * 64, (r % 64) * 32, lane); continue; } r -= IT_GLA;
;                     if (r < IT_FN) { transpose_item(a.in[I_WFN], FNW, DM, WfnT, (r % 64) * 32, scr, (r / 64) * 64, (r % 64) * 32, lane); continue; } r -= IT_FN;
.LBB0_950:
	s_waitcnt lgkmcnt(0)
	ds_read2_b32 v[22:23], v24 offset0:33 offset1:41
	ds_read2_b32 v[32:33], v24 offset1:8
	ds_read2_b32 v[34:35], v24 offset0:66 offset1:74
	ds_read2_b32 v[36:37], v24 offset0:99 offset1:107
	ds_read2_b32 v[38:39], v24 offset0:132 offset1:140
	ds_read2_b32 v[40:41], v24 offset0:165 offset1:173
	ds_read2_b32 v[42:43], v24 offset0:198 offset1:206
	ds_read2_b32 v[44:45], v24 offset0:231 offset1:239
	s_mov_b32 s5, s3
	v_or_b32_e32 v2, s10, v7
	v_lshl_add_u64 v[46:47], s[4:5], 1, v[20:21]
	v_lshlrev_b32_e32 v2, 11, v2
	s_waitcnt lgkmcnt(6)
	v_cvt_pk_bf16_f32 v28, v32, v22
	s_waitcnt lgkmcnt(4)
	v_cvt_pk_bf16_f32 v29, v34, v36
	s_waitcnt lgkmcnt(2)
	v_cvt_pk_bf16_f32 v30, v38, v40
	s_waitcnt lgkmcnt(0)
	v_cvt_pk_bf16_f32 v31, v42, v44
	v_lshl_add_u64 v[48:49], v[46:47], 0, v[2:3]
	global_store_dwordx4 v[48:49], v[28:31], off sc1
	v_or_b32_e32 v2, s10, v25
	v_lshlrev_b32_e32 v2, 11, v2
	v_cvt_pk_bf16_f32 v28, v33, v23
	v_cvt_pk_bf16_f32 v29, v35, v37
	v_cvt_pk_bf16_f32 v30, v39, v41
	v_cvt_pk_bf16_f32 v31, v43, v45
	ds_read2_b32 v[32:33], v24 offset0:49 offset1:57
	ds_read2_b32 v[34:35], v24 offset0:16 offset1:24
	ds_read2_b32 v[36:37], v24 offset0:82 offset1:90
	ds_read2_b32 v[38:39], v24 offset0:115 offset1:123
	ds_read2_b32 v[40:41], v24 offset0:148 offset1:156
	ds_read2_b32 v[42:43], v24 offset0:181 offset1:189
	ds_read2_b32 v[44:45], v24 offset0:214 offset1:222
	ds_read2_b32 v[48:49], v24 offset0:247 offset1:255
	v_lshl_add_u64 v[22:23], v[46:47], 0, v[2:3]
	v_or_b32_e32 v2, s10, v26
	v_lshlrev_b32_e32 v2, 11, v2
	global_store_dwordx4 v[22:23], v[28:31], off sc1
	v_lshl_add_u64 v[22:23], v[46:47], 0, v[2:3]
	v_or_b32_e32 v2, s10, v27
	s_waitcnt lgkmcnt(6)
	v_cvt_pk_bf16_f32 v28, v34, v32
	s_waitcnt lgkmcnt(4)
	v_cvt_pk_bf16_f32 v29, v36, v38
	s_waitcnt lgkmcnt(2)
	v_cvt_pk_bf16_f32 v30, v40, v42
	s_waitcnt lgkmcnt(0)
	v_cvt_pk_bf16_f32 v31, v44, v48
	v_lshlrev_b32_e32 v2, 11, v2
	global_store_dwordx4 v[22:23], v[28:31], off sc1
	v_lshl_add_u64 v[22:23], v[46:47], 0, v[2:3]
	s_nop 0
	v_cvt_pk_bf16_f32 v28, v35, v33
	v_cvt_pk_bf16_f32 v29, v37, v39
	v_cvt_pk_bf16_f32 v30, v41, v43
	v_cvt_pk_bf16_f32 v31, v45, v49
	global_store_dwordx4 v[22:23], v[28:31], off sc1
	s_waitcnt lgkmcnt(0)

; #define LAS __attribute__((address_space(3)))
; __device__ __forceinline__ unsigned pk2(float lo, float hi) { return pk2hw(lo, hi); }
; __device__ __forceinline__ void transpose_item(const float* W, int K, int N, bf16_t* WT, int drow0, LAS float* scr, int k0, int n0, int lane) {
;     ...
;     for (int i = 0; i < 32; ++i) { const int kk = 2 * i + (lane >> 5); scr[kk * 33 + (lane & 31)] = W[(size_t)(k0 + kk) * N + n0 + (lane & 31)]; }
;     asm volatile("s_waitcnt lgkmcnt(0)" ::: "memory");
;     const int c = lane & 7;
; #pragma unroll
;     for (int j = 0; j < 4; ++j) { const int n = (lane >> 3) + 8 * j; const LAS float* s = scr + (8 * c) * 33 + n;
;         u32x4 o; o.x = pk2(s[0 * 33], s[1 * 33]); o.y = pk2(s[2 * 33], s[3 * 33]); o.z = pk2(s[4 * 33], s[5 * 33]); o.w = pk2(s[6 * 33], s[7 * 33]);
;         *(u32x4*)(WT + (size_t)(drow0 + n) * K + k0 + 8 * c) = o; }
; __global__ void __launch_bounds__(NTHR, 2) fwd_kernel(Args a) {
;     ...
;                 if (r < IT_UP) { const int n0 = (r % 352) * 32, j = n0 < FF ? n0 : n0 - FF; transpose_item(a.in[I_WUP], DM, F2, WupT, (j >> 7) * 256 + (n0 < FF ? 0 : 128) + (j & 127), scr, (r / 352) * 64, n0, lane); continue; } r -= IT_UP;
.LBB0_954:
	s_lshl_b32 s22, s11, 1
	s_lshl_b32 s23, s20, 1
	v_or_b32_e32 v2, s22, v1
	v_or_b32_e32 v60, s23, v0
	s_add_i32 s24, s22, 4
	s_add_i32 s25, s23, 4
	s_add_i32 s26, s22, 8
	s_add_i32 s27, s23, 8
	s_add_i32 s28, s22, 12
	s_add_i32 s29, s23, 12
	s_add_i32 s30, s22, 16
	s_add_i32 s31, s23, 16
	s_add_i32 s33, s22, 20
	s_add_i32 s34, s23, 20
	s_add_i32 s35, s22, 24
	s_add_i32 s36, s23, 24
	s_add_i32 s22, s22, 28
	s_add_i32 s23, s23, 28
	v_add_u32_e32 v28, s4, v60
	v_or_b32_e32 v61, s24, v1
	v_or_b32_e32 v62, s25, v0
	v_or_b32_e32 v63, s26, v1
	v_or_b32_e32 v64, s27, v0
	v_or_b32_e32 v65, s28, v1
	v_or_b32_e32 v66, s29, v0
	v_or_b32_e32 v67, s30, v1
	v_or_b32_e32 v68, s31, v0
	v_or_b32_e32 v69, s33, v1
	v_or_b32_e32 v70, s34, v0
	v_or_b32_e32 v71, s35, v1
	v_or_b32_e32 v72, s36, v0
	v_or_b32_e32 v73, s22, v1
	v_or_b32_e32 v74, s23, v0
	v_add_u32_e32 v30, s5, v2
	v_mad_i64_i32 v[28:29], s[22:23], v28, s19, v[22:23]
	v_add_u32_e32 v34, s5, v61
	v_add_u32_e32 v32, s4, v62
	v_add_u32_e32 v38, s5, v63
	v_add_u32_e32 v36, s4, v64
	v_add_u32_e32 v42, s5, v65
	v_add_u32_e32 v40, s4, v66
	v_add_u32_e32 v46, s5, v67
	v_add_u32_e32 v44, s4, v68
	v_add_u32_e32 v50, s5, v69
	v_add_u32_e32 v48, s4, v70
	v_add_u32_e32 v54, s5, v71
	v_add_u32_e32 v52, s4, v72
	v_add_u32_e32 v58, s5, v73
	v_add_u32_e32 v56, s4, v74
	v_mad_i64_i32 v[30:31], s[22:23], v30, s19, v[22:23]
	v_mad_i64_i32 v[32:33], s[22:23], v32, s19, v[22:23]
	v_mad_i64_i32 v[34:35], s[22:23], v34, s19, v[22:23]
	v_mad_i64_i32 v[36:37], s[22:23], v36, s19, v[22:23]
	v_mad_i64_i32 v[38:39], s[22:23], v38, s19, v[22:23]
	v_mad_i64_i32 v[40:41], s[22:23], v40, s19, v[22:23]
	v_mad_i64_i32 v[42:43], s[22:23], v42, s19, v[22:23]
	v_mad_i64_i32 v[44:45], s[22:23], v44, s19, v[22:23]
	v_mad_i64_i32 v[46:47], s[22:23], v46, s19, v[22:23]
	v_mad_i64_i32 v[48:49], s[22:23], v48, s19, v[22:23]
	v_mad_i64_i32 v[50:51], s[22:23], v50, s19, v[22:23]
	v_mad_i64_i32 v[52:53], s[22:23], v52, s19, v[22:23]
	v_mad_i64_i32 v[54:55], s[22:23], v54, s19, v[22:23]
	v_mad_i64_i32 v[56:57], s[22:23], v56, s19, v[22:23]
	v_mad_i64_i32 v[58:59], s[22:23], v58, s19, v[22:23]
	global_load_dword v75, v[28:29], off
	global_load_dword v76, v[30:31], off
	global_load_dword v77, v[32:33], off
	global_load_dword v78, v[34:35], off
	global_load_dword v79, v[36:37], off
	global_load_dword v80, v[38:39], off
	global_load_dword v81, v[40:41], off
	global_load_dword v82, v[42:43], off
	global_load_dword v83, v[44:45], off
	global_load_dword v84, v[46:47], off
	global_load_dword v85, v[48:49], off
	global_load_dword v86, v[50:51], off
	global_load_dword v87, v[52:53], off
	global_load_dword v88, v[54:55], off
	global_load_dword v89, v[56:57], off
	global_load_dword v90, v[58:59], off
	s_add_i32 s20, s20, 16
	s_add_i32 s11, s11, 16
	s_add_i32 s21, s21, -16
	v_mad_u64_u32 v[28:29], s[22:23], v60, s18, v[6:7]
	s_cmp_lg_u32 s21, 0
	v_mad_u64_u32 v[30:31], s[22:23], v2, s18, v[6:7]
	v_mad_u64_u32 v[32:33], s[22:23], v62, s18, v[6:7]
	v_mad_u64_u32 v[34:35], s[22:23], v61, s18, v[6:7]
	v_mad_u64_u32 v[36:37], s[22:23], v64, s18, v[6:7]
	v_mad_u64_u32 v[38:39], s[22:23], v63, s18, v[6:7]
	v_mad_u64_u32 v[40:41], s[22:23], v66, s18, v[6:7]
	v_mad_u64_u32 v[42:43], s[22:23], v65, s18, v[6:7]
	v_mad_u64_u32 v[44:45], s[22:23], v68, s18, v[6:7]
	v_mad_u64_u32 v[46:47], s[22:23], v67, s18, v[6:7]
	v_mad_u64_u32 v[48:49], s[22:23], v70, s18, v[6:7]
	v_mad_u64_u32 v[50:51], s[22:23], v69, s18, v[6:7]
	v_mad_u64_u32 v[52:53], s[22:23], v72, s18, v[6:7]
	v_mad_u64_u32 v[54:55], s[22:23], v71, s18, v[6:7]
	v_mad_u64_u32 v[56:57], s[22:23], v74, s18, v[6:7]
	v_mad_u64_u32 v[58:59], s[22:23], v73, s18, v[6:7]
	s_waitcnt vmcnt(0)
	ds_write_b32 v28, v75
	ds_write_b32 v30, v76
	ds_write_b32 v32, v77
	ds_write_b32 v34, v78
	ds_write_b32 v36, v79
	ds_write_b32 v38, v80
	ds_write_b32 v40, v81
	ds_write_b32 v42, v82
	ds_write_b32 v44, v83
	ds_write_b32 v46, v84
	ds_write_b32 v48, v85
	ds_write_b32 v50, v86
	ds_write_b32 v52, v87
	ds_write_b32 v54, v88
	ds_write_b32 v56, v89
	ds_write_b32 v58, v90
	s_cbranch_scc1 .LBB0_954
	s_add_i32 s5, s10, 0xffffea00
	s_cmpk_lt_i32 s2, 0xb0
	s_cselect_b32 s2, s10, s5
	s_cselect_b32 s5, 0, 0x80
	s_lshl_b32 s10, s2, 1
	s_and_b32 s2, s2, 0x60
	s_waitcnt lgkmcnt(0)
	s_or_b32 s2, s2, s5
	s_and_b32 s5, s10, 0xffffff00
	ds_read2_b32 v[22:23], v24 offset0:33 offset1:41
	ds_read2_b32 v[32:33], v24 offset1:8
	ds_read2_b32 v[34:35], v24 offset0:66 offset1:74
	ds_read2_b32 v[36:37], v24 offset0:99 offset1:107
	ds_read2_b32 v[38:39], v24 offset0:132 offset1:140
	ds_read2_b32 v[40:41], v24 offset0:165 offset1:173
	ds_read2_b32 v[42:43], v24 offset0:198 offset1:206
	ds_read2_b32 v[44:45], v24 offset0:231 offset1:239
	s_or_b32 s2, s2, s5
	v_or_b32_e32 v48, s2, v7
	s_ashr_i32 s5, s4, 31
	v_ashrrev_i32_e32 v49, 31, v48
	v_lshl_add_u64 v[46:47], s[4:5], 1, v[8:9]
	v_lshlrev_b64 v[48:49], 12, v[48:49]
	s_waitcnt lgkmcnt(6)
	v_cvt_pk_bf16_f32 v28, v32, v22
	s_waitcnt lgkmcnt(4)
	v_cvt_pk_bf16_f32 v29, v34, v36
	s_waitcnt lgkmcnt(2)
	v_cvt_pk_bf16_f32 v30, v38, v40
	s_waitcnt lgkmcnt(0)
	v_cvt_pk_bf16_f32 v31, v42, v44
	v_lshl_add_u64 v[48:49], v[46:47], 0, v[48:49]
	v_or_b32_e32 v22, s2, v25
	global_store_dwordx4 v[48:49], v[28:31], off sc1
	s_mov_b64 s[4:5], 0
	s_nop 0
	v_cvt_pk_bf16_f32 v28, v33, v23
	v_ashrrev_i32_e32 v23, 31, v22
	v_cvt_pk_bf16_f32 v29, v35, v37
	v_cvt_pk_bf16_f32 v30, v39, v41
	v_cvt_pk_bf16_f32 v31, v43, v45
	v_lshlrev_b64 v[22:23], 12, v[22:23]
	ds_read2_b32 v[32:33], v24 offset0:49 offset1:57
	ds_read2_b32 v[34:35], v24 offset0:16 offset1:24
	ds_read2_b32 v[36:37], v24 offset0:82 offset1:90
	ds_read2_b32 v[38:39], v24 offset0:115 offset1:123
	ds_read2_b32 v[40:41], v24 offset0:148 offset1:156
	ds_read2_b32 v[42:43], v24 offset0:181 offset1:189
	ds_read2_b32 v[44:45], v24 offset0:214 offset1:222
	ds_read2_b32 v[48:49], v24 offset0:247 offset1:255
	v_lshl_add_u64 v[22:23], v[46:47], 0, v[22:23]
	global_store_dwordx4 v[22:23], v[28:31], off sc1
	v_or_b32_e32 v22, s2, v26
	v_ashrrev_i32_e32 v23, 31, v22
	v_lshlrev_b64 v[22:23], 12, v[22:23]
	s_waitcnt lgkmcnt(6)
	v_cvt_pk_bf16_f32 v28, v34, v32
	s_waitcnt lgkmcnt(4)
	v_cvt_pk_bf16_f32 v29, v36, v38
	s_waitcnt lgkmcnt(2)
	v_cvt_pk_bf16_f32 v30, v40, v42
	s_waitcnt lgkmcnt(0)
	v_cvt_pk_bf16_f32 v31, v44, v48
	v_lshl_add_u64 v[22:23], v[46:47], 0, v[22:23]
	global_store_dwordx4 v[22:23], v[28:31], off sc1
	v_or_b32_e32 v22, s2, v27
	v_ashrrev_i32_e32 v23, 31, v22
	v_lshlrev_b64 v[22:23], 12, v[22:23]
	v_cvt_pk_bf16_f32 v28, v35, v33
	v_cvt_pk_bf16_f32 v29, v37, v39
	v_cvt_pk_bf16_f32 v30, v41, v43
	v_cvt_pk_bf16_f32 v31, v45, v49
	v_lshl_add_u64 v[22:23], v[46:47], 0, v[22:23]
	global_store_dwordx4 v[22:23], v[28:31], off sc1
	s_waitcnt lgkmcnt(0)

; __device__ __forceinline__ void transpose_item(const float* W, int K, int N, bf16_t* WT, int drow0, LAS float* scr, int k0, int n0, int lane) {
; #pragma unroll 8
;     for (int i = 0; i < 32; ++i) { const int kk = 2 * i + (lane >> 5); scr[kk * 33 + (lane & 31)] = W[(size_t)(k0 + kk) * N + n0 + (lane & 31)]; }
;     asm volatile("s_waitcnt lgkmcnt(0)" ::: "memory");
.LBB0_960:
	s_lshl_b32 s21, s5, 1
	s_lshl_b32 s22, s11, 1
	v_or_b32_e32 v2, s21, v1
	v_or_b32_e32 v60, s22, v0
	s_add_i32 s23, s21, 4
	s_add_i32 s24, s22, 4
	s_add_i32 s25, s21, 8
	s_add_i32 s26, s22, 8
	s_add_i32 s27, s21, 12
	s_add_i32 s28, s22, 12
	s_add_i32 s29, s21, 16
	s_add_i32 s30, s22, 16
	s_add_i32 s31, s21, 20
	s_add_i32 s33, s22, 20
	s_add_i32 s34, s21, 24
	s_add_i32 s35, s22, 24
	s_add_i32 s21, s21, 28
	s_add_i32 s22, s22, 28
	v_add_u32_e32 v30, s4, v60
	v_or_b32_e32 v61, s23, v1
	v_or_b32_e32 v62, s24, v0
	v_or_b32_e32 v63, s25, v1
	v_or_b32_e32 v64, s26, v0
	v_or_b32_e32 v65, s27, v1
	v_or_b32_e32 v66, s28, v0
	v_or_b32_e32 v67, s29, v1
	v_or_b32_e32 v68, s30, v0
	v_or_b32_e32 v69, s31, v1
	v_or_b32_e32 v70, s33, v0
	v_or_b32_e32 v71, s34, v1
	v_or_b32_e32 v72, s35, v0
	v_or_b32_e32 v73, s21, v1
	v_or_b32_e32 v74, s22, v0
	v_add_u32_e32 v28, s2, v2
	v_ashrrev_i32_e32 v31, 31, v30
	v_add_u32_e32 v32, s2, v61
	v_add_u32_e32 v34, s4, v62
	v_add_u32_e32 v36, s2, v63
	v_add_u32_e32 v38, s4, v64
	v_add_u32_e32 v40, s2, v65
	v_add_u32_e32 v42, s4, v66
	v_add_u32_e32 v44, s2, v67
	v_add_u32_e32 v46, s4, v68
	v_add_u32_e32 v48, s2, v69
	v_add_u32_e32 v50, s4, v70
	v_add_u32_e32 v52, s2, v71
	v_add_u32_e32 v54, s4, v72
	v_add_u32_e32 v56, s2, v73
	v_add_u32_e32 v58, s4, v74
	v_ashrrev_i32_e32 v29, 31, v28
	v_lshlrev_b64 v[30:31], 13, v[30:31]
	v_ashrrev_i32_e32 v35, 31, v34
	v_ashrrev_i32_e32 v33, 31, v32
	v_ashrrev_i32_e32 v39, 31, v38
	v_ashrrev_i32_e32 v37, 31, v36
	v_ashrrev_i32_e32 v43, 31, v42
	v_ashrrev_i32_e32 v41, 31, v40
	v_ashrrev_i32_e32 v47, 31, v46
	v_ashrrev_i32_e32 v45, 31, v44
	v_ashrrev_i32_e32 v51, 31, v50
	v_ashrrev_i32_e32 v49, 31, v48
	v_ashrrev_i32_e32 v55, 31, v54
	v_ashrrev_i32_e32 v53, 31, v52
	v_ashrrev_i32_e32 v59, 31, v58
	v_ashrrev_i32_e32 v57, 31, v56
	v_lshlrev_b64 v[28:29], 13, v[28:29]
	v_lshl_add_u64 v[30:31], v[22:23], 0, v[30:31]
	v_lshlrev_b64 v[32:33], 13, v[32:33]
	v_lshlrev_b64 v[34:35], 13, v[34:35]
	v_lshlrev_b64 v[36:37], 13, v[36:37]
	v_lshlrev_b64 v[38:39], 13, v[38:39]
	v_lshlrev_b64 v[40:41], 13, v[40:41]
	v_lshlrev_b64 v[42:43], 13, v[42:43]
	v_lshlrev_b64 v[44:45], 13, v[44:45]
	v_lshlrev_b64 v[46:47], 13, v[46:47]
	v_lshlrev_b64 v[48:49], 13, v[48:49]
	v_lshlrev_b64 v[50:51], 13, v[50:51]
	v_lshlrev_b64 v[52:53], 13, v[52:53]
	v_lshlrev_b64 v[54:55], 13, v[54:55]
	v_lshlrev_b64 v[56:57], 13, v[56:57]
	v_lshlrev_b64 v[58:59], 13, v[58:59]
	v_lshl_add_u64 v[28:29], v[22:23], 0, v[28:29]
	v_lshl_add_u64 v[34:35], v[22:23], 0, v[34:35]
	v_lshl_add_u64 v[32:33], v[22:23], 0, v[32:33]
	v_lshl_add_u64 v[38:39], v[22:23], 0, v[38:39]
	v_lshl_add_u64 v[36:37], v[22:23], 0, v[36:37]
	v_lshl_add_u64 v[42:43], v[22:23], 0, v[42:43]
	v_lshl_add_u64 v[40:41], v[22:23], 0, v[40:41]
	v_lshl_add_u64 v[46:47], v[22:23], 0, v[46:47]
	v_lshl_add_u64 v[44:45], v[22:23], 0, v[44:45]
	v_lshl_add_u64 v[50:51], v[22:23], 0, v[50:51]
	v_lshl_add_u64 v[48:49], v[22:23], 0, v[48:49]
	v_lshl_add_u64 v[54:55], v[22:23], 0, v[54:55]
	v_lshl_add_u64 v[52:53], v[22:23], 0, v[52:53]
	v_lshl_add_u64 v[58:59], v[22:23], 0, v[58:59]
	v_lshl_add_u64 v[56:57], v[22:23], 0, v[56:57]
	global_load_dword v75, v[30:31], off
	global_load_dword v76, v[28:29], off
	global_load_dword v77, v[34:35], off
	global_load_dword v78, v[32:33], off
	global_load_dword v79, v[38:39], off
	global_load_dword v80, v[36:37], off
	global_load_dword v81, v[42:43], off
	global_load_dword v82, v[40:41], off
	global_load_dword v83, v[46:47], off
	global_load_dword v84, v[44:45], off
	global_load_dword v85, v[50:51], off
	global_load_dword v86, v[48:49], off
	global_load_dword v87, v[54:55], off
	global_load_dword v88, v[52:53], off
	global_load_dword v89, v[58:59], off
	global_load_dword v90, v[56:57], off
	s_add_i32 s11, s11, 16
	s_add_i32 s5, s5, 16
	s_add_i32 s20, s20, -16
	v_mad_u64_u32 v[28:29], s[22:23], v60, s18, v[6:7]
	s_cmp_lg_u32 s20, 0
	v_mad_u64_u32 v[30:31], s[22:23], v2, s18, v[6:7]
	v_mad_u64_u32 v[32:33], s[22:23], v62, s18, v[6:7]
	v_mad_u64_u32 v[34:35], s[22:23], v61, s18, v[6:7]
	v_mad_u64_u32 v[36:37], s[22:23], v64, s18, v[6:7]
	v_mad_u64_u32 v[38:39], s[22:23], v63, s18, v[6:7]
	v_mad_u64_u32 v[40:41], s[22:23], v66, s18, v[6:7]
	v_mad_u64_u32 v[42:43], s[22:23], v65, s18, v[6:7]
	v_mad_u64_u32 v[44:45], s[22:23], v68, s18, v[6:7]
	v_mad_u64_u32 v[46:47], s[22:23], v67, s18, v[6:7]
	v_mad_u64_u32 v[48:49], s[22:23], v70, s18, v[6:7]
	v_mad_u64_u32 v[50:51], s[22:23], v69, s18, v[6:7]
	v_mad_u64_u32 v[52:53], s[22:23], v72, s18, v[6:7]
	v_mad_u64_u32 v[54:55], s[22:23], v71, s18, v[6:7]
	v_mad_u64_u32 v[56:57], s[22:23], v74, s18, v[6:7]
	v_mad_u64_u32 v[58:59], s[22:23], v73, s18, v[6:7]
	s_waitcnt vmcnt(0)
	ds_write_b32 v28, v75
	ds_write_b32 v30, v76
	ds_write_b32 v32, v77
	ds_write_b32 v34, v78
	ds_write_b32 v36, v79
	ds_write_b32 v38, v80
	ds_write_b32 v40, v81
	ds_write_b32 v42, v82
	ds_write_b32 v44, v83
	ds_write_b32 v46, v84
	ds_write_b32 v48, v85
	ds_write_b32 v50, v86
	ds_write_b32 v52, v87
	ds_write_b32 v54, v88
	ds_write_b32 v56, v89
	ds_write_b32 v58, v90
	s_cbranch_scc1 .LBB0_960
; #define LAS __attribute__((address_space(3)))
; __device__ __forceinline__ unsigned pk2(float lo, float hi) { return pk2hw(lo, hi); }
; __device__ __forceinline__ void transpose_item(const float* W, int K, int N, bf16_t* WT, int drow0, LAS float* scr, int k0, int n0, int lane) {
;     ...
;     const int c = lane & 7;
; #pragma unroll
;     for (int j = 0; j < 4; ++j) { const int n = (lane >> 3) + 8 * j; const LAS float* s = scr + (8 * c) * 33 + n;
;         u32x4 o; o.x = pk2(s[0 * 33], s[1 * 33]); o.y = pk2(s[2 * 33], s[3 * 33]); o.z = pk2(s[4 * 33], s[5 * 33]); o.w = pk2(s[6 * 33], s[7 * 33]);
;         *(u32x4*)(WT + (size_t)(drow0 + n) * K + k0 + 8 * c) = o; }
; __global__ void __launch_bounds__(NTHR, 2) fwd_kernel(Args a) {
;     ...
;                     transpose_item(a.in[I_WOUT], DM, DM, WoT, (r % 64) * 32, scr, (r / 64) * 64, (r % 64) * 32, lane); continue; }
	s_waitcnt lgkmcnt(0)
	ds_read2_b32 v[22:23], v24 offset0:33 offset1:41
	ds_read2_b32 v[32:33], v24 offset1:8
	ds_read2_b32 v[34:35], v24 offset0:66 offset1:74
	ds_read2_b32 v[36:37], v24 offset0:99 offset1:107
	ds_read2_b32 v[38:39], v24 offset0:132 offset1:140
	ds_read2_b32 v[40:41], v24 offset0:165 offset1:173
	ds_read2_b32 v[42:43], v24 offset0:198 offset1:206
	ds_read2_b32 v[44:45], v24 offset0:231 offset1:239
	s_mov_b32 s5, s3
	v_or_b32_e32 v2, s10, v7
	v_lshl_add_u64 v[46:47], s[4:5], 1, v[12:13]
	v_lshlrev_b32_e32 v2, 12, v2
	s_waitcnt lgkmcnt(6)
	v_cvt_pk_bf16_f32 v28, v32, v22
	s_waitcnt lgkmcnt(4)
	v_cvt_pk_bf16_f32 v29, v34, v36
	s_waitcnt lgkmcnt(2)
	v_cvt_pk_bf16_f32 v30, v38, v40
	s_waitcnt lgkmcnt(0)
	v_cvt_pk_bf16_f32 v31, v42, v44
	v_lshl_add_u64 v[48:49], v[46:47], 0, v[2:3]
	global_store_dwordx4 v[48:49], v[28:31], off sc1
	v_or_b32_e32 v2, s10, v25
	v_lshlrev_b32_e32 v2, 12, v2
	v_cvt_pk_bf16_f32 v28, v33, v23
	v_cvt_pk_bf16_f32 v29, v35, v37
	v_cvt_pk_bf16_f32 v30, v39, v41
	v_cvt_pk_bf16_f32 v31, v43, v45
	ds_read2_b32 v[32:33], v24 offset0:49 offset1:57
	ds_read2_b32 v[34:35], v24 offset0:16 offset1:24
	ds_read2_b32 v[36:37], v24 offset0:82 offset1:90
	ds_read2_b32 v[38:39], v24 offset0:115 offset1:123
	ds_read2_b32 v[40:41], v24 offset0:148 offset1:156
	ds_read2_b32 v[42:43], v24 offset0:181 offset1:189
	ds_read2_b32 v[44:45], v24 offset0:214 offset1:222
	ds_read2_b32 v[48:49], v24 offset0:247 offset1:255
	v_lshl_add_u64 v[22:23], v[46:47], 0, v[2:3]
	v_or_b32_e32 v2, s10, v26
	v_lshlrev_b32_e32 v2, 12, v2
	global_store_dwordx4 v[22:23], v[28:31], off sc1
	v_lshl_add_u64 v[22:23], v[46:47], 0, v[2:3]
	v_or_b32_e32 v2, s10, v27
	s_waitcnt lgkmcnt(6)
	v_cvt_pk_bf16_f32 v28, v34, v32
	s_waitcnt lgkmcnt(4)
	v_cvt_pk_bf16_f32 v29, v36, v38
	s_waitcnt lgkmcnt(2)
	v_cvt_pk_bf16_f32 v30, v40, v42
	s_waitcnt lgkmcnt(0)
	v_cvt_pk_bf16_f32 v31, v44, v48
	v_lshlrev_b32_e32 v2, 12, v2
	global_store_dwordx4 v[22:23], v[28:31], off sc1
	v_lshl_add_u64 v[22:23], v[46:47], 0, v[2:3]
	s_mov_b64 s[4:5], 0
	v_cvt_pk_bf16_f32 v28, v35, v33
	v_cvt_pk_bf16_f32 v29, v37, v39
	v_cvt_pk_bf16_f32 v30, v41, v43
	v_cvt_pk_bf16_f32 v31, v45, v49
	global_store_dwordx4 v[22:23], v[28:31], off sc1
	s_waitcnt lgkmcnt(0)

; __device__ __forceinline__ void transpose_item(const float* W, int K, int N, bf16_t* WT, int drow0, LAS float* scr, int k0, int n0, int lane) {
; #pragma unroll 8
;     for (int i = 0; i < 32; ++i) { const int kk = 2 * i + (lane >> 5); scr[kk * 33 + (lane & 31)] = W[(size_t)(k0 + kk) * N + n0 + (lane & 31)]; }
;     asm volatile("s_waitcnt lgkmcnt(0)" ::: "memory");
.LBB0_964:
	s_lshl_b32 s21, s5, 1
	s_lshl_b32 s22, s11, 1
	v_or_b32_e32 v2, s21, v1
	v_or_b32_e32 v60, s22, v0
	s_add_i32 s23, s21, 4
	s_add_i32 s24, s22, 4
	s_add_i32 s25, s21, 8
	s_add_i32 s26, s22, 8
	s_add_i32 s27, s21, 12
	s_add_i32 s28, s22, 12
	s_add_i32 s29, s21, 16
	s_add_i32 s30, s22, 16
	s_add_i32 s31, s21, 20
	s_add_i32 s33, s22, 20
	s_add_i32 s34, s21, 24
	s_add_i32 s35, s22, 24
	s_add_i32 s21, s21, 28
	s_add_i32 s22, s22, 28
	v_add_u32_e32 v30, s4, v60
	v_or_b32_e32 v61, s23, v1
	v_or_b32_e32 v62, s24, v0
	v_or_b32_e32 v63, s25, v1
	v_or_b32_e32 v64, s26, v0
	v_or_b32_e32 v65, s27, v1
	v_or_b32_e32 v66, s28, v0
	v_or_b32_e32 v67, s29, v1
	v_or_b32_e32 v68, s30, v0
	v_or_b32_e32 v69, s31, v1
	v_or_b32_e32 v70, s33, v0
	v_or_b32_e32 v71, s34, v1
	v_or_b32_e32 v72, s35, v0
	v_or_b32_e32 v73, s21, v1
	v_or_b32_e32 v74, s22, v0
	v_add_u32_e32 v28, s2, v2
	v_ashrrev_i32_e32 v31, 31, v30
	v_add_u32_e32 v32, s2, v61
	v_add_u32_e32 v34, s4, v62
	v_add_u32_e32 v36, s2, v63
	v_add_u32_e32 v38, s4, v64
	v_add_u32_e32 v40, s2, v65
	v_add_u32_e32 v42, s4, v66
	v_add_u32_e32 v44, s2, v67
	v_add_u32_e32 v46, s4, v68
	v_add_u32_e32 v48, s2, v69
	v_add_u32_e32 v50, s4, v70
	v_add_u32_e32 v52, s2, v71
	v_add_u32_e32 v54, s4, v72
	v_add_u32_e32 v56, s2, v73
	v_add_u32_e32 v58, s4, v74
	v_ashrrev_i32_e32 v29, 31, v28
	v_lshlrev_b64 v[30:31], 13, v[30:31]
	v_ashrrev_i32_e32 v35, 31, v34
	v_ashrrev_i32_e32 v33, 31, v32
	v_ashrrev_i32_e32 v39, 31, v38
	v_ashrrev_i32_e32 v37, 31, v36
	v_ashrrev_i32_e32 v43, 31, v42
	v_ashrrev_i32_e32 v41, 31, v40
	v_ashrrev_i32_e32 v47, 31, v46
	v_ashrrev_i32_e32 v45, 31, v44
	v_ashrrev_i32_e32 v51, 31, v50
	v_ashrrev_i32_e32 v49, 31, v48
	v_ashrrev_i32_e32 v55, 31, v54
	v_ashrrev_i32_e32 v53, 31, v52
	v_ashrrev_i32_e32 v59, 31, v58
	v_ashrrev_i32_e32 v57, 31, v56
	v_lshlrev_b64 v[28:29], 13, v[28:29]
	v_lshl_add_u64 v[30:31], v[22:23], 0, v[30:31]
	v_lshlrev_b64 v[32:33], 13, v[32:33]
	v_lshlrev_b64 v[34:35], 13, v[34:35]
	v_lshlrev_b64 v[36:37], 13, v[36:37]
	v_lshlrev_b64 v[38:39], 13, v[38:39]
	v_lshlrev_b64 v[40:41], 13, v[40:41]
	v_lshlrev_b64 v[42:43], 13, v[42:43]
	v_lshlrev_b64 v[44:45], 13, v[44:45]
	v_lshlrev_b64 v[46:47], 13, v[46:47]
	v_lshlrev_b64 v[48:49], 13, v[48:49]
	v_lshlrev_b64 v[50:51], 13, v[50:51]
	v_lshlrev_b64 v[52:53], 13, v[52:53]
	v_lshlrev_b64 v[54:55], 13, v[54:55]
	v_lshlrev_b64 v[56:57], 13, v[56:57]
	v_lshlrev_b64 v[58:59], 13, v[58:59]
	v_lshl_add_u64 v[28:29], v[22:23], 0, v[28:29]
	v_lshl_add_u64 v[34:35], v[22:23], 0, v[34:35]
	v_lshl_add_u64 v[32:33], v[22:23], 0, v[32:33]
	v_lshl_add_u64 v[38:39], v[22:23], 0, v[38:39]
	v_lshl_add_u64 v[36:37], v[22:23], 0, v[36:37]
	v_lshl_add_u64 v[42:43], v[22:23], 0, v[42:43]
	v_lshl_add_u64 v[40:41], v[22:23], 0, v[40:41]
	v_lshl_add_u64 v[46:47], v[22:23], 0, v[46:47]
	v_lshl_add_u64 v[44:45], v[22:23], 0, v[44:45]
	v_lshl_add_u64 v[50:51], v[22:23], 0, v[50:51]
	v_lshl_add_u64 v[48:49], v[22:23], 0, v[48:49]
	v_lshl_add_u64 v[54:55], v[22:23], 0, v[54:55]
	v_lshl_add_u64 v[52:53], v[22:23], 0, v[52:53]
	v_lshl_add_u64 v[58:59], v[22:23], 0, v[58:59]
	v_lshl_add_u64 v[56:57], v[22:23], 0, v[56:57]
	global_load_dword v75, v[30:31], off
	global_load_dword v76, v[28:29], off
	global_load_dword v77, v[34:35], off
	global_load_dword v78, v[32:33], off
	global_load_dword v79, v[38:39], off
	global_load_dword v80, v[36:37], off
	global_load_dword v81, v[42:43], off
	global_load_dword v82, v[40:41], off
	global_load_dword v83, v[46:47], off
	global_load_dword v84, v[44:45], off
	global_load_dword v85, v[50:51], off
	global_load_dword v86, v[48:49], off
	global_load_dword v87, v[54:55], off
	global_load_dword v88, v[52:53], off
	global_load_dword v89, v[58:59], off
	global_load_dword v90, v[56:57], off
	s_add_i32 s11, s11, 16
	s_add_i32 s5, s5, 16
	s_add_i32 s20, s20, -16
	v_mad_u64_u32 v[28:29], s[22:23], v60, s18, v[6:7]
	s_cmp_lg_u32 s20, 0
	v_mad_u64_u32 v[30:31], s[22:23], v2, s18, v[6:7]
	v_mad_u64_u32 v[32:33], s[22:23], v62, s18, v[6:7]
	v_mad_u64_u32 v[34:35], s[22:23], v61, s18, v[6:7]
	v_mad_u64_u32 v[36:37], s[22:23], v64, s18, v[6:7]
	v_mad_u64_u32 v[38:39], s[22:23], v63, s18, v[6:7]
	v_mad_u64_u32 v[40:41], s[22:23], v66, s18, v[6:7]
	v_mad_u64_u32 v[42:43], s[22:23], v65, s18, v[6:7]
	v_mad_u64_u32 v[44:45], s[22:23], v68, s18, v[6:7]
	v_mad_u64_u32 v[46:47], s[22:23], v67, s18, v[6:7]
	v_mad_u64_u32 v[48:49], s[22:23], v70, s18, v[6:7]
	v_mad_u64_u32 v[50:51], s[22:23], v69, s18, v[6:7]
	v_mad_u64_u32 v[52:53], s[22:23], v72, s18, v[6:7]
	v_mad_u64_u32 v[54:55], s[22:23], v71, s18, v[6:7]
	v_mad_u64_u32 v[56:57], s[22:23], v74, s18, v[6:7]
	v_mad_u64_u32 v[58:59], s[22:23], v73, s18, v[6:7]
	s_waitcnt vmcnt(0)
	ds_write_b32 v28, v75
	ds_write_b32 v30, v76
	ds_write_b32 v32, v77
	ds_write_b32 v34, v78
	ds_write_b32 v36, v79
	ds_write_b32 v38, v80
	ds_write_b32 v40, v81
	ds_write_b32 v42, v82
	ds_write_b32 v44, v83
	ds_write_b32 v46, v84
	ds_write_b32 v48, v85
	ds_write_b32 v50, v86
	ds_write_b32 v52, v87
	ds_write_b32 v54, v88
	ds_write_b32 v56, v89
	ds_write_b32 v58, v90
	s_cbranch_scc1 .LBB0_964
; #define LAS __attribute__((address_space(3)))
; __device__ __forceinline__ unsigned pk2(float lo, float hi) { return pk2hw(lo, hi); }
; __device__ __forceinline__ void transpose_item(const float* W, int K, int N, bf16_t* WT, int drow0, LAS float* scr, int k0, int n0, int lane) {
;     ...
;     const int c = lane & 7;
; #pragma unroll
;     for (int j = 0; j < 4; ++j) { const int n = (lane >> 3) + 8 * j; const LAS float* s = scr + (8 * c) * 33 + n;
;         u32x4 o; o.x = pk2(s[0 * 33], s[1 * 33]); o.y = pk2(s[2 * 33], s[3 * 33]); o.z = pk2(s[4 * 33], s[5 * 33]); o.w = pk2(s[6 * 33], s[7 * 33]);
;         *(u32x4*)(WT + (size_t)(drow0 + n) * K + k0 + 8 * c) = o; }
; __global__ void __launch_bounds__(NTHR, 2) fwd_kernel(Args a) {
;     ...
;                     if (r < IT_GLA) { transpose_item(a.in[I_WGLA], VW, DM, WglaT, (r % 64) * 32, scr, (r / 64) * 64, (r % 64) * 32, lane); continue; } r -= IT_GLA;
;                     if (r < IT_FN) { transpose_item(a.in[I_WFN], FNW, DM, WfnT, (r % 64) * 32, scr, (r / 64) * 64, (r % 64) * 32, lane); continue; } r -= IT_FN;
	s_waitcnt lgkmcnt(0)
	ds_read2_b32 v[22:23], v24 offset0:33 offset1:41
	ds_read2_b32 v[32:33], v24 offset1:8
	ds_read2_b32 v[34:35], v24 offset0:66 offset1:74
	ds_read2_b32 v[36:37], v24 offset0:99 offset1:107
	ds_read2_b32 v[38:39], v24 offset0:132 offset1:140
	ds_read2_b32 v[40:41], v24 offset0:165 offset1:173
	ds_read2_b32 v[42:43], v24 offset0:198 offset1:206
	ds_read2_b32 v[44:45], v24 offset0:231 offset1:239
	s_mov_b32 s5, s3
	v_or_b32_e32 v2, s10, v7
	v_lshl_add_u64 v[46:47], s[4:5], 1, v[16:17]
	v_lshlrev_b32_e32 v2, 11, v2
	s_waitcnt lgkmcnt(6)
	v_cvt_pk_bf16_f32 v28, v32, v22
	s_waitcnt lgkmcnt(4)
	v_cvt_pk_bf16_f32 v29, v34, v36
	s_waitcnt lgkmcnt(2)
	v_cvt_pk_bf16_f32 v30, v38, v40
	s_waitcnt lgkmcnt(0)
	v_cvt_pk_bf16_f32 v31, v42, v44
	v_lshl_add_u64 v[48:49], v[46:47], 0, v[2:3]
	global_store_dwordx4 v[48:49], v[28:31], off sc1
	v_or_b32_e32 v2, s10, v25
	v_lshlrev_b32_e32 v2, 11, v2
	v_cvt_pk_bf16_f32 v28, v33, v23
	v_cvt_pk_bf16_f32 v29, v35, v37
	v_cvt_pk_bf16_f32 v30, v39, v41
	v_cvt_pk_bf16_f32 v31, v43, v45
	ds_read2_b32 v[32:33], v24 offset0:49 offset1:57
	ds_read2_b32 v[34:35], v24 offset0:16 offset1:24
	ds_read2_b32 v[36:37], v24 offset0:82 offset1:90
	ds_read2_b32 v[38:39], v24 offset0:115 offset1:123
	ds_read2_b32 v[40:41], v24 offset0:148 offset1:156
	ds_read2_b32 v[42:43], v24 offset0:181 offset1:189
	ds_read2_b32 v[44:45], v24 offset0:214 offset1:222
	ds_read2_b32 v[48:49], v24 offset0:247 offset1:255
	v_lshl_add_u64 v[22:23], v[46:47], 0, v[2:3]
	v_or_b32_e32 v2, s10, v26
	v_lshlrev_b32_e32 v2, 11, v2
	global_store_dwordx4 v[22:23], v[28:31], off sc1
	v_lshl_add_u64 v[22:23], v[46:47], 0, v[2:3]
	v_or_b32_e32 v2, s10, v27
	s_waitcnt lgkmcnt(6)
	v_cvt_pk_bf16_f32 v28, v34, v32
	s_waitcnt lgkmcnt(4)
	v_cvt_pk_bf16_f32 v29, v36, v38
	s_waitcnt lgkmcnt(2)
	v_cvt_pk_bf16_f32 v30, v40, v42
	s_waitcnt lgkmcnt(0)
	v_cvt_pk_bf16_f32 v31, v44, v48
	v_lshlrev_b32_e32 v2, 11, v2
	global_store_dwordx4 v[22:23], v[28:31], off sc1
	v_lshl_add_u64 v[22:23], v[46:47], 0, v[2:3]
	s_nop 0
	v_cvt_pk_bf16_f32 v28, v35, v33
	v_cvt_pk_bf16_f32 v29, v37, v39
	v_cvt_pk_bf16_f32 v30, v41, v43
	v_cvt_pk_bf16_f32 v31, v45, v49
	global_store_dwordx4 v[22:23], v[28:31], off sc1
	s_waitcnt lgkmcnt(0)
